# retention loop: post-barrier LDS read bursts reordered by first use, lgkmcnt recounted from data dependences
# speedup vs baseline: 1.0002x; 1.0002x over previous
.LBB0_1370:
	s_add_i32 s1, s57, -1
	s_waitcnt vmcnt(7)
	ds_write_b128 v175, v[72:75]
	ds_write_b128 v175, v[68:71] offset:8704
	ds_write_b128 v175, v[64:67] offset:17408
	v_cndmask_b32_e32 v65, v180, v173, vcc
	v_xor_b32_e32 v66, 0xffffffef, v173
	v_xor_b32_e32 v70, 0xffffffcf, v173
	s_min_u32 s18, s1, s0
	v_add_u32_e32 v69, 48, v173
	v_xor_b32_e32 v67, 0xffffffdf, v173
	v_add_u32_e32 v71, s55, v66
	v_add_u32_e32 v66, s56, v65
	v_add_u32_e32 v70, s55, v70
	v_lshl_add_u32 v73, s18, 5, v174
	v_add_u32_e32 v64, 16, v173
	v_add_u32_e32 v68, 32, v173
	v_add_u32_e32 v65, s55, v67
	v_ashrrev_i32_e32 v67, 31, v66
	v_cndmask_b32_e32 v69, v70, v69, vcc
	v_xad_u32 v70, v73, -1, s55
	v_cndmask_b32_e32 v71, v71, v64, vcc
	v_cndmask_b32_e32 v68, v65, v68, vcc
	v_lshlrev_b64 v[64:65], 11, v[66:67]
	v_cndmask_b32_e32 v67, v70, v73, vcc
	s_min_u32 s42, s57, s0
	v_lshl_add_u64 v[242:243], v[170:171], 0, v[64:65]
	v_add_u32_e32 v64, s56, v67
	v_lshl_add_u32 v72, s42, 5, v174
	v_ashrrev_i32_e32 v65, 31, v64
	v_cvt_pk_bf16_f32 v60, v44, v45
	v_cvt_pk_bf16_f32 v61, v46, v47
	v_cvt_pk_bf16_f32 v62, v40, v41
	v_cvt_pk_bf16_f32 v63, v42, v43
	v_xad_u32 v74, v72, -1, s55
	v_lshlrev_b64 v[64:65], 13, v[64:65]
	v_cndmask_b32_e32 v66, v74, v72, vcc
	v_or_b32_e32 v64, v64, v181
	v_add_u32_e32 v238, s56, v68
	v_add_u32_e32 v240, s56, v69
	v_add_u32_e32 v244, s56, v66
	v_lshl_add_u64 v[66:67], s[36:37], 0, v[64:65]
	v_lshl_add_u64 v[68:69], s[38:39], 0, v[64:65]
	v_lshl_add_u64 v[64:65], s[40:41], 0, v[64:65]
	v_add_u32_e32 v0, 0x1000, v178
	v_add_u32_e32 v1, 0x2000, v179
	v_add_u32_e32 v182, 0x3000, v179
	v_add_u32_e32 v236, s56, v71
	global_load_dwordx4 v[72:75], v[66:67], off
	s_nop 0
	global_load_dwordx4 v[68:71], v[68:69], off
	s_nop 0
	global_load_dwordx4 v[64:67], v[64:65], off
	s_waitcnt lgkmcnt(0)
	s_barrier
	ds_read_b64_tr_b16 v[212:213], v177 offset:17408
	ds_read_b64_tr_b16 v[214:215], v177 offset:21760
	ds_read_b64 v[192:193], v0 offset:256
	ds_read_b64 v[194:195], v0 offset:288
	ds_read_b64 v[188:189], v178
	ds_read_b64 v[190:191], v178 offset:32
	ds_read_b64 v[200:201], v1 offset:512
	ds_read_b64 v[202:203], v1 offset:544
	ds_read_b64 v[204:205], v182 offset:768
	ds_read_b64 v[206:207], v182 offset:800
	ds_read_b64_tr_b16 v[210:211], v176 offset:13056
	ds_read_b64_tr_b16 v[208:209], v176 offset:8704
	ds_read_b64_tr_b16 v[216:217], v176 offset:8736
	ds_read_b64_tr_b16 v[218:219], v176 offset:13088
	ds_read_b64_tr_b16 v[220:221], v176 offset:8768
	ds_read_b64_tr_b16 v[222:223], v176 offset:13120
	ds_read_b64_tr_b16 v[230:231], v176 offset:8928
	ds_read_b64 v[196:197], v0 offset:320
	ds_read_b64 v[198:199], v0 offset:352
	s_waitcnt lgkmcnt(15)
	v_lshlrev_b32_e32 v232, 16, v212
	v_and_b32_e32 v233, 0xffff0000, v212
	v_lshlrev_b32_e32 v234, 16, v213
	v_and_b32_e32 v235, 0xffff0000, v213
	v_lshlrev_b32_e32 v246, 16, v214
	v_and_b32_e32 v247, 0xffff0000, v214
	v_lshlrev_b32_e32 v248, 16, v215
	v_and_b32_e32 v249, 0xffff0000, v215
	v_mov_b32_e32 v159, v158
	v_mfma_f32_16x16x32_bf16 v[226:229], v[60:63], v[192:195], 0
	v_mul_f32_e64 v232, v150, v232
	v_mul_f32_e64 v233, v151, v233
	v_pk_mul_f32 v[234:235], v[152:153], v[234:235]
	v_pk_mul_f32 v[44:45], v[164:165], v[44:45]
	s_waitcnt lgkmcnt(13)
	v_mfma_f32_16x16x32_bf16 v[60:63], v[60:63], v[188:191], 0
	v_mul_f32_e64 v46, v158, v46
	v_mul_f32_e64 v47, v159, v47
	v_pk_mul_f32 v[40:41], v[164:165], v[40:41]
	v_pk_mul_f32 v[42:43], v[158:159], v[42:43]
	s_waitcnt lgkmcnt(11)
	v_mfma_f32_16x16x32_bf16 v[188:191], v[200:203], v[188:191], 0
	v_cvt_pk_bf16_f32 v52, v36, v37
	v_cvt_pk_bf16_f32 v53, v38, v39
	v_cvt_pk_bf16_f32 v54, v32, v33
	v_mfma_f32_16x16x32_bf16 v[200:203], v[200:203], v[192:195], 0
	v_cvt_pk_bf16_f32 v55, v34, v35
	v_cvt_pk_bf16_f32 v56, v28, v29
	v_cvt_pk_bf16_f32 v57, v30, v31
	s_waitcnt lgkmcnt(9)
	v_mfma_f32_16x16x32_bf16 v[192:195], v[204:207], v[192:195], 0
	v_mul_f32_e64 v206, v154, v246
	v_mul_f32_e64 v207, v155, v247
	v_pk_mul_f32 v[246:247], v[156:157], v[248:249]
	v_cvt_pk_bf16_f32 v204, v232, v233
	v_cvt_pk_bf16_f32 v205, v234, v235
	v_cvt_pk_bf16_f32 v206, v206, v207
	v_cvt_pk_bf16_f32 v207, v246, v247
	v_pk_mul_f32 v[36:37], v[164:165], v[36:37]
	v_pk_mul_f32 v[32:33], v[164:165], v[32:33]
	s_waitcnt lgkmcnt(7)
	v_mfma_f32_16x16x32_bf16 v[44:47], v[208:211], v[204:207], v[44:47]
	ds_read_b64_tr_b16 v[210:211], v176 offset:13152
	ds_read_b64_tr_b16 v[208:209], v176 offset:8800
	ds_read_b64_tr_b16 v[232:233], v176 offset:8832
	v_pk_mul_f32 v[28:29], v[164:165], v[28:29]
	v_pk_mul_f32 v[38:39], v[158:159], v[38:39]
	s_waitcnt lgkmcnt(8)
	v_mfma_f32_16x16x32_bf16 v[40:43], v[216:219], v[204:207], v[40:43]
	ds_read_b64_tr_b16 v[216:217], v176 offset:8864
	ds_read_b64_tr_b16 v[234:235], v176 offset:13184
	ds_read_b64_tr_b16 v[218:219], v176 offset:13216
	v_pk_mul_f32 v[34:35], v[158:159], v[34:35]
	v_pk_mul_f32 v[30:31], v[158:159], v[30:31]
	s_waitcnt lgkmcnt(9)
	v_mfma_f32_16x16x32_bf16 v[36:39], v[220:223], v[204:207], v[36:39]
	v_ashrrev_i32_e32 v245, 31, v244
	v_ashrrev_i32_e32 v237, 31, v236
	v_cvt_pk_bf16_f32 v58, v24, v25
	s_waitcnt lgkmcnt(4)
	v_mfma_f32_16x16x32_bf16 v[32:35], v[208:211], v[204:207], v[32:35]
	ds_read_b64_tr_b16 v[208:209], v176 offset:8896
	ds_read_b64_tr_b16 v[210:211], v176 offset:13248
	v_cvt_pk_bf16_f32 v59, v26, v27
	s_waitcnt lgkmcnt(3)
	v_mfma_f32_16x16x32_bf16 v[220:223], v[232:235], v[204:207], v[28:31]
	ds_read_b64_tr_b16 v[232:233], v176 offset:13280
	v_cvt_pk_bf16_f32 v48, v20, v21
	v_cvt_pk_bf16_f32 v49, v22, v23
	v_lshlrev_b64 v[28:29], 13, v[244:245]
	v_cvt_pk_bf16_f32 v50, v16, v17
	v_cvt_pk_bf16_f32 v51, v18, v19
	v_pk_mul_f32 v[24:25], v[164:165], v[24:25]
	v_pk_mul_f32 v[20:21], v[164:165], v[20:21]
	v_pk_mul_f32 v[16:17], v[164:165], v[16:17]
	v_pk_mul_f32 v[26:27], v[158:159], v[26:27]
	v_pk_mul_f32 v[22:23], v[158:159], v[22:23]
	v_pk_mul_f32 v[18:19], v[158:159], v[18:19]
	v_ashrrev_i32_e32 v239, 31, v238
	v_ashrrev_i32_e32 v241, 31, v240
	v_lshlrev_b64 v[236:237], 11, v[236:237]
	v_or_b32_e32 v28, v28, v181
	v_lshlrev_b64 v[246:247], 11, v[238:239]
	v_lshlrev_b64 v[248:249], 11, v[240:241]
	s_waitcnt lgkmcnt(3)
	v_mfma_f32_16x16x32_bf16 v[216:219], v[216:219], v[204:207], v[24:27]
	v_lshl_add_u64 v[234:235], v[170:171], 0, v[236:237]
	v_lshl_add_u64 v[236:237], s[36:37], 0, v[28:29]
	v_lshl_add_u64 v[238:239], s[38:39], 0, v[28:29]
	s_waitcnt lgkmcnt(1)
	v_mfma_f32_16x16x32_bf16 v[208:211], v[208:211], v[204:207], v[20:23]
	ds_read_b64 v[24:25], v1 offset:576
	ds_read_b64 v[26:27], v1 offset:608
	v_lshl_add_u64 v[240:241], s[40:41], 0, v[28:29]
	ds_read_b64 v[28:29], v182 offset:832
	ds_read_b64 v[30:31], v182 offset:864
	s_waitcnt lgkmcnt(4)
	v_mfma_f32_16x16x32_bf16 v[204:207], v[230:233], v[204:207], v[16:19]
	v_mov_b32_e32 v3, v2
	v_add_u32_e32 v183, 0x6000, v178
	v_add_u32_e32 v184, 0x7000, v178
	ds_read_b64 v[16:17], v178 offset:64
	ds_read_b64 v[18:19], v178 offset:96
	v_mfma_f32_16x16x32_bf16 v[226:229], v[52:55], v[196:199], v[226:229]
	v_add_u32_e32 v185, 0x8800, v179
	v_add_u32_e32 v186, 0x9800, v179
	s_add_i32 s57, s57, 2
	s_waitcnt lgkmcnt(0)
	v_mfma_f32_16x16x32_bf16 v[20:23], v[52:55], v[16:19], v[60:63]
	ds_read_b64 v[52:53], v0 offset:384
	ds_read_b64 v[54:55], v0 offset:416
	s_nop 1
	ds_read_b64 v[60:61], v178 offset:128
	ds_read_b64 v[62:63], v178 offset:160
	v_add_u32_e32 v173, 64, v173
	v_subrev_u32_e32 v180, 64, v180
	v_mfma_f32_16x16x32_bf16 v[16:19], v[24:27], v[16:19], v[188:191]
	s_cmp_ge_u32 s1, s58
	v_mfma_f32_16x16x32_bf16 v[24:27], v[24:27], v[196:199], v[200:203]
	v_mfma_f32_16x16x32_bf16 v[28:31], v[28:31], v[196:199], v[192:195]
	s_nop 2
	ds_read_b64 v[192:193], v1 offset:640
	ds_read_b64 v[194:195], v1 offset:672
	ds_read_b64 v[196:197], v178 offset:192
	ds_read_b64 v[198:199], v178 offset:224
	ds_read_b64 v[200:201], v0 offset:448
	ds_read_b64 v[202:203], v0 offset:480
	s_waitcnt lgkmcnt(8)
	v_mfma_f32_16x16x32_bf16 v[188:191], v[56:59], v[52:55], v[226:229]
	s_waitcnt lgkmcnt(6)
	v_mfma_f32_16x16x32_bf16 v[20:23], v[56:59], v[60:63], v[20:23]
	ds_read_b64 v[56:57], v182 offset:896
	ds_read_b64 v[58:59], v182 offset:928
	ds_read_b64 v[226:227], v1 offset:704
	ds_read_b64 v[228:229], v1 offset:736
	ds_read_b64 v[230:231], v182 offset:960
	ds_read_b64 v[232:233], v182 offset:992
	s_waitcnt vmcnt(5)
	ds_write_b128 v175, v[12:15] offset:26112
	ds_write_b128 v175, v[8:11] offset:34816
	ds_write_b128 v175, v[4:7] offset:43520
	s_waitcnt lgkmcnt(13)
	v_mfma_f32_16x16x32_bf16 v[16:19], v[192:195], v[60:63], v[16:19]
	v_mfma_f32_16x16x32_bf16 v[4:7], v[192:195], v[52:55], v[24:27]
	s_waitcnt lgkmcnt(7)
	v_mfma_f32_16x16x32_bf16 v[8:11], v[56:59], v[52:55], v[28:31]
	s_nop 0
	v_cvt_pk_bf16_f32 v24, v44, v45
	v_cvt_pk_bf16_f32 v25, v46, v47
	v_cvt_pk_bf16_f32 v26, v40, v41
	s_waitcnt lgkmcnt(5)
	v_mfma_f32_16x16x32_bf16 v[16:19], v[226:229], v[196:199], v[16:19]
	v_mul_f32_e64 v28, v164, v44
	v_mul_f32_e64 v29, v165, v45
	v_cvt_pk_bf16_f32 v27, v42, v43
	v_pk_mul_f32 v[30:31], v[158:159], v[46:47]
	v_mfma_f32_16x16x32_bf16 v[4:7], v[226:229], v[200:203], v[4:7]
	v_cvt_pk_bf16_f32 v52, v36, v37
	s_nop 1
	v_pk_mul_f32 v[18:19], v[146:147], v[18:19]
	v_pk_mul_f32 v[0:1], v[142:143], v[16:17]
	s_waitcnt lgkmcnt(3)
	v_mfma_f32_16x16x32_bf16 v[8:11], v[230:233], v[200:203], v[8:11]
	v_cvt_pk_bf16_f32 v0, v0, v1
	v_pk_mul_f32 v[6:7], v[148:149], v[6:7]
	v_pk_mul_f32 v[4:5], v[144:145], v[4:5]
	v_cvt_pk_bf16_f32 v1, v18, v19
	v_cvt_pk_bf16_f32 v4, v4, v5
	s_nop 2
	v_pk_mul_f32 v[16:17], v[146:147], v[10:11]
	v_pk_mul_f32 v[44:45], v[142:143], v[8:9]
	v_cvt_pk_bf16_f32 v5, v6, v7
	v_cvt_pk_bf16_f32 v6, v44, v45
	v_cvt_pk_bf16_f32 v7, v16, v17
	v_mfma_f32_16x16x32_bf16 v[12:15], v[48:51], v[200:203], v[188:191]
	v_cvt_pk_bf16_f32 v53, v38, v39
	v_pk_mul_f32 v[38:39], v[158:159], v[38:39]
	v_pk_mul_f32 v[36:37], v[164:165], v[36:37]
	v_mfma_f32_16x16x32_bf16 v[20:23], v[48:51], v[196:199], v[20:23]
	v_cvt_pk_bf16_f32 v54, v32, v33
	v_cvt_pk_bf16_f32 v55, v34, v35
	v_pk_mul_f32 v[42:43], v[158:159], v[42:43]
	v_mfma_f32_16x16x32_bf16 v[8:11], v[212:215], v[0:3], 0
	v_mul_f32_e64 v40, v164, v40
	v_mul_f32_e64 v41, v165, v41
	v_pk_mul_f32 v[34:35], v[158:159], v[34:35]
	v_pk_mul_f32 v[32:33], v[164:165], v[32:33]
	v_mfma_f32_16x16x32_bf16 v[4:7], v[212:215], v[4:7], 0
	v_mul_f32_e64 v50, v158, v222
	v_mul_f32_e64 v51, v159, v223
	s_nop 0
	v_pk_fma_f32 v[8:9], v[162:163], v[20:21], v[8:9]
	v_pk_mul_f32 v[48:49], v[164:165], v[220:221]
	v_cvt_pk_bf16_f32 v8, v8, v9
	v_cvt_pk_bf16_f32 v56, v220, v221
	s_nop 0
	v_pk_fma_f32 v[0:1], v[166:167], v[14:15], v[6:7]
	v_pk_fma_f32 v[6:7], v[168:169], v[22:23], v[10:11]
	v_pk_fma_f32 v[4:5], v[160:161], v[12:13], v[4:5]
	v_cvt_pk_bf16_f32 v9, v6, v7
	v_cvt_pk_bf16_f32 v4, v4, v5
	v_cvt_pk_bf16_f32 v5, v0, v1
	global_store_dwordx2 v[242:243], v[8:9], off
	global_store_dwordx2 v[234:235], v[4:5], off
	global_load_dwordx4 v[12:15], v[236:237], off
	s_nop 0
	global_load_dwordx4 v[8:11], v[238:239], off
	global_load_dwordx4 v[4:7], v[240:241], off
	s_waitcnt lgkmcnt(0)
	s_barrier
	ds_read_b64 v[20:21], v184 offset:1792
	ds_read_b64 v[22:23], v184 offset:1824
	ds_read_b64_tr_b16 v[196:197], v177 offset:43520
	ds_read_b64 v[16:17], v183 offset:1536
	ds_read_b64 v[18:19], v183 offset:1568
	ds_read_b64 v[44:45], v185
	ds_read_b64 v[46:47], v185 offset:32
	ds_read_b64_tr_b16 v[198:199], v177 offset:47872
	ds_read_b64 v[188:189], v186 offset:256
	ds_read_b64 v[190:191], v186 offset:288
	ds_read_b64_tr_b16 v[194:195], v176 offset:39168
	ds_read_b64_tr_b16 v[192:193], v176 offset:34816
	ds_read_b64_tr_b16 v[212:213], v176 offset:34880
	ds_read_b64_tr_b16 v[214:215], v176 offset:39232
	ds_read_b64_tr_b16 v[200:201], v176 offset:34848
	ds_read_b64 v[60:61], v184 offset:1856
	ds_read_b64 v[62:63], v184 offset:1888
	s_waitcnt lgkmcnt(15)
	v_mfma_f32_16x16x32_bf16 v[226:229], v[24:27], v[20:23], 0
	s_waitcnt lgkmcnt(14)
	v_lshlrev_b32_e32 v0, 16, v196
	v_and_b32_e32 v1, 0xffff0000, v196
	v_pk_mul_f32 v[0:1], v[150:151], v[0:1]
	s_waitcnt lgkmcnt(12)
	v_mfma_f32_16x16x32_bf16 v[234:237], v[24:27], v[16:19], 0
	v_lshlrev_b32_e32 v24, 16, v197
	v_and_b32_e32 v25, 0xffff0000, v197
	v_pk_mul_f32 v[24:25], v[152:153], v[24:25]
	s_waitcnt lgkmcnt(10)
	v_mfma_f32_16x16x32_bf16 v[238:241], v[44:47], v[16:19], 0
	s_waitcnt lgkmcnt(9)
	v_lshlrev_b32_e32 v16, 16, v198
	v_and_b32_e32 v17, 0xffff0000, v198
	v_lshlrev_b32_e32 v18, 16, v199
	v_and_b32_e32 v19, 0xffff0000, v199
	v_mfma_f32_16x16x32_bf16 v[242:245], v[44:47], v[20:23], 0
	ds_read_b64_tr_b16 v[202:203], v176 offset:39200
	ds_read_b64_tr_b16 v[230:231], v176 offset:35040
	v_cvt_pk_bf16_f32 v57, v222, v223
	v_cvt_pk_bf16_f32 v58, v216, v217
	s_waitcnt lgkmcnt(9)
	v_mfma_f32_16x16x32_bf16 v[188:191], v[188:191], v[20:23], 0
	v_mul_f32_e64 v20, v154, v16
	v_mul_f32_e64 v21, v155, v17
	v_pk_mul_f32 v[22:23], v[156:157], v[18:19]
	v_cvt_pk_bf16_f32 v16, v0, v1
	v_cvt_pk_bf16_f32 v17, v24, v25
	v_cvt_pk_bf16_f32 v18, v20, v21
	v_cvt_pk_bf16_f32 v19, v22, v23
	ds_read_b64_tr_b16 v[22:23], v176 offset:39264
	ds_read_b64_tr_b16 v[20:21], v176 offset:34912
	ds_read_b64_tr_b16 v[24:25], v176 offset:34944
	s_waitcnt lgkmcnt(10)
	v_mfma_f32_16x16x32_bf16 v[44:47], v[192:195], v[16:19], v[28:31]
	ds_read_b64_tr_b16 v[192:193], v176 offset:34976
	ds_read_b64_tr_b16 v[26:27], v176 offset:39296
	ds_read_b64_tr_b16 v[194:195], v176 offset:39328
	ds_read_b64_tr_b16 v[232:233], v176 offset:39392
	v_cvt_pk_bf16_f32 v59, v218, v219
	s_waitcnt lgkmcnt(12)
	v_mfma_f32_16x16x32_bf16 v[36:39], v[212:215], v[16:19], v[36:39]
	ds_read_b64_tr_b16 v[212:213], v176 offset:35008
	ds_read_b64_tr_b16 v[214:215], v176 offset:39360
	s_waitcnt lgkmcnt(10)
	v_mfma_f32_16x16x32_bf16 v[40:43], v[200:203], v[16:19], v[40:43]
	v_mul_f32_e64 v202, v158, v218
	v_mul_f32_e64 v203, v159, v219
	v_pk_mul_f32 v[200:201], v[164:165], v[216:217]
	ds_read_b64 v[216:217], v183 offset:1664
	ds_read_b64 v[218:219], v183 offset:1696
	s_waitcnt lgkmcnt(9)
	v_mfma_f32_16x16x32_bf16 v[32:35], v[20:23], v[16:19], v[32:35]
	v_mul_f32_e64 v22, v158, v210
	v_mul_f32_e64 v23, v159, v211
	v_pk_mul_f32 v[20:21], v[164:165], v[208:209]
	s_waitcnt lgkmcnt(6)
	v_mfma_f32_16x16x32_bf16 v[28:31], v[24:27], v[16:19], v[48:51]
	s_waitcnt lgkmcnt(5)
	v_mfma_f32_16x16x32_bf16 v[24:27], v[192:195], v[16:19], v[200:203]
	ds_read_b64 v[192:193], v185 offset:64
	ds_read_b64 v[194:195], v185 offset:96
	v_pk_mul_f32 v[50:51], v[158:159], v[206:207]
	v_pk_mul_f32 v[48:49], v[164:165], v[204:205]
	s_waitcnt lgkmcnt(4)
	v_mfma_f32_16x16x32_bf16 v[20:23], v[212:215], v[16:19], v[20:23]
	ds_read_b64 v[212:213], v186 offset:320
	ds_read_b64 v[214:215], v186 offset:352
	v_cvt_pk_bf16_f32 v202, v204, v205
	v_cvt_pk_bf16_f32 v203, v206, v207
	v_mfma_f32_16x16x32_bf16 v[16:19], v[230:233], v[16:19], v[48:51]
	ds_read_b64 v[204:205], v183 offset:1728
	ds_read_b64 v[206:207], v183 offset:1760
	v_cvt_pk_bf16_f32 v200, v208, v209
	v_cvt_pk_bf16_f32 v201, v210, v211
	ds_read_b64 v[48:49], v183 offset:1600
	ds_read_b64 v[50:51], v183 offset:1632
	v_mfma_f32_16x16x32_bf16 v[226:229], v[52:55], v[60:63], v[226:229]
	s_waitcnt lgkmcnt(0)
	v_mfma_f32_16x16x32_bf16 v[52:55], v[52:55], v[48:51], v[234:237]
	v_mfma_f32_16x16x32_bf16 v[48:51], v[192:195], v[48:51], v[238:241]
	v_mfma_f32_16x16x32_bf16 v[192:195], v[192:195], v[60:63], v[242:245]
	v_mfma_f32_16x16x32_bf16 v[60:63], v[212:215], v[60:63], v[188:191]
	s_nop 2
	ds_read_b64 v[188:189], v184 offset:1920
	ds_read_b64 v[190:191], v184 offset:1952
	s_waitcnt lgkmcnt(0)
	v_mfma_f32_16x16x32_bf16 v[212:215], v[56:59], v[188:191], v[226:229]
	v_mfma_f32_16x16x32_bf16 v[52:55], v[56:59], v[216:219], v[52:55]
	ds_read_b64 v[56:57], v185 offset:128
	ds_read_b64 v[58:59], v185 offset:160
	s_waitcnt lgkmcnt(0)
	v_mfma_f32_16x16x32_bf16 v[48:51], v[56:59], v[216:219], v[48:51]
	v_mfma_f32_16x16x32_bf16 v[56:59], v[56:59], v[188:191], v[192:195]
	s_nop 2
	ds_read_b64 v[192:193], v186 offset:384
	ds_read_b64 v[194:195], v186 offset:416
	s_waitcnt lgkmcnt(0)
	v_mfma_f32_16x16x32_bf16 v[60:63], v[192:195], v[188:191], v[60:63]
	ds_read_b64 v[188:189], v184 offset:1984
	ds_read_b64 v[190:191], v184 offset:2016
	ds_read_b64 v[182:183], v185 offset:192
	ds_read_b64 v[184:185], v185 offset:224
	s_waitcnt lgkmcnt(0)
	v_mfma_f32_16x16x32_bf16 v[48:51], v[182:185], v[204:207], v[48:51]
	s_nop 7
	v_pk_mul_f32 v[50:51], v[146:147], v[50:51]
	v_mfma_f32_16x16x32_bf16 v[56:59], v[182:185], v[188:191], v[56:59]
	ds_read_b64 v[182:183], v186 offset:448
	ds_read_b64 v[184:185], v186 offset:480
	v_pk_mul_f32 v[0:1], v[142:143], v[48:49]
	s_waitcnt lgkmcnt(0)
	v_mfma_f32_16x16x32_bf16 v[60:63], v[182:185], v[188:191], v[60:63]
	s_nop 3
	v_mul_f32_e64 v182, v148, v58
	v_mul_f32_e64 v183, v149, v59
	v_pk_mul_f32 v[48:49], v[144:145], v[56:57]
	v_cvt_pk_bf16_f32 v0, v0, v1
	v_pk_mul_f32 v[62:63], v[146:147], v[62:63]
	v_pk_mul_f32 v[60:61], v[142:143], v[60:61]
	v_cvt_pk_bf16_f32 v1, v50, v51
	v_cvt_pk_bf16_f32 v48, v48, v49
	v_cvt_pk_bf16_f32 v49, v182, v183
	v_cvt_pk_bf16_f32 v50, v60, v61
	v_cvt_pk_bf16_f32 v51, v62, v63
	v_mfma_f32_16x16x32_bf16 v[192:195], v[200:203], v[188:191], v[212:215]
	v_mfma_f32_16x16x32_bf16 v[52:55], v[200:203], v[204:207], v[52:55]
	v_lshl_add_u64 v[200:201], v[170:171], 0, v[246:247]
	v_lshl_add_u64 v[202:203], v[170:171], 0, v[248:249]
	v_mfma_f32_16x16x32_bf16 v[56:59], v[196:199], v[0:3], 0
	v_mfma_f32_16x16x32_bf16 v[48:51], v[196:199], v[48:51], 0
	s_nop 6
	v_fma_f32 v52, v162, v52, v56
	v_fma_f32 v53, v163, v53, v57
	v_pk_fma_f32 v[0:1], v[166:167], v[194:195], v[50:51]
	v_pk_fma_f32 v[50:51], v[168:169], v[54:55], v[58:59]
	v_pk_fma_f32 v[48:49], v[160:161], v[192:193], v[48:49]
	v_cvt_pk_bf16_f32 v52, v52, v53
	v_cvt_pk_bf16_f32 v53, v50, v51
	v_cvt_pk_bf16_f32 v48, v48, v49
	v_cvt_pk_bf16_f32 v49, v0, v1
	global_store_dwordx2 v[200:201], v[52:53], off
	global_store_dwordx2 v[202:203], v[48:49], off
	s_cbranch_scc0 .LBB0_1370
	s_andn2_b64 vcc, exec, s[6:7]
	s_cbranch_vccnz .LBB0_1354
	s_add_u32 s0, s28, s14
	s_addc_u32 s1, s29, s15
	v_lshl_add_u64 v[0:1], v[112:113], 2, s[0:1]
	s_waitcnt vmcnt(2)
	v_lshl_add_u64 v[4:5], v[0:1], 0, v[76:77]
	global_store_dword v[4:5], v44, off nt
	v_lshl_add_u64 v[4:5], v[0:1], 0, v[78:79]
	global_store_dword v[4:5], v45, off nt
	v_lshl_add_u64 v[4:5], v[0:1], 0, v[80:81]
	global_store_dword v[4:5], v46, off nt
	v_lshl_add_u64 v[4:5], v[0:1], 0, v[82:83]
	global_store_dword v[4:5], v47, off nt
	v_lshl_add_u64 v[4:5], v[0:1], 0, v[84:85]
	global_store_dword v[4:5], v40, off nt
	v_lshl_add_u64 v[4:5], v[0:1], 0, v[86:87]
	global_store_dword v[4:5], v41, off nt
	v_lshl_add_u64 v[4:5], v[0:1], 0, v[88:89]
	global_store_dword v[4:5], v42, off nt
	v_lshl_add_u64 v[4:5], v[0:1], 0, v[90:91]
	global_store_dword v[4:5], v43, off nt
	v_lshl_add_u64 v[4:5], v[0:1], 0, v[92:93]
	global_store_dword v[4:5], v36, off nt
	v_lshl_add_u64 v[4:5], v[0:1], 0, v[94:95]
	global_store_dword v[4:5], v37, off nt
	v_lshl_add_u64 v[4:5], v[0:1], 0, v[96:97]
	global_store_dword v[4:5], v38, off nt
	v_lshl_add_u64 v[4:5], v[0:1], 0, v[98:99]
	global_store_dword v[4:5], v39, off nt
	v_lshl_add_u64 v[4:5], v[0:1], 0, v[100:101]
	global_store_dword v[4:5], v32, off nt
	v_lshl_add_u64 v[4:5], v[0:1], 0, v[102:103]
	global_store_dword v[4:5], v33, off nt
	v_lshl_add_u64 v[4:5], v[0:1], 0, v[104:105]
	global_store_dword v[4:5], v34, off nt
	v_lshl_add_u64 v[4:5], v[0:1], 0, v[106:107]
	global_store_dword v[4:5], v35, off nt
	v_lshl_add_u64 v[4:5], v[0:1], 0, v[108:109]
	global_store_dword v[4:5], v28, off nt
	v_lshl_add_u64 v[4:5], v[0:1], 0, v[110:111]
	global_store_dword v[4:5], v29, off nt
	v_lshl_add_u64 v[4:5], v[0:1], 0, v[138:139]
	global_store_dword v[4:5], v30, off nt
	v_lshl_add_u64 v[4:5], v[0:1], 0, v[136:137]
	global_store_dword v[4:5], v31, off nt
	v_lshl_add_u64 v[4:5], v[0:1], 0, v[134:135]
	global_store_dword v[4:5], v24, off nt
	v_lshl_add_u64 v[4:5], v[0:1], 0, v[132:133]
	global_store_dword v[4:5], v25, off nt
	v_lshl_add_u64 v[4:5], v[0:1], 0, v[130:131]
	global_store_dword v[4:5], v26, off nt
	v_lshl_add_u64 v[4:5], v[0:1], 0, v[128:129]
	global_store_dword v[4:5], v27, off nt
	v_lshl_add_u64 v[4:5], v[0:1], 0, v[126:127]
	global_store_dword v[4:5], v20, off nt
	v_lshl_add_u64 v[4:5], v[0:1], 0, v[124:125]
	global_store_dword v[4:5], v21, off nt
	v_lshl_add_u64 v[4:5], v[0:1], 0, v[122:123]
	global_store_dword v[4:5], v22, off nt
	v_lshl_add_u64 v[4:5], v[0:1], 0, v[120:121]
	global_store_dword v[4:5], v23, off nt
	v_lshl_add_u64 v[4:5], v[0:1], 0, v[118:119]
	global_store_dword v[4:5], v16, off nt
	v_lshl_add_u64 v[4:5], v[0:1], 0, v[116:117]
	global_store_dword v[4:5], v17, off nt
	v_lshl_add_u64 v[4:5], v[0:1], 0, v[114:115]
	v_lshl_add_u64 v[0:1], v[0:1], 0, v[140:141]
	global_store_dword v[4:5], v18, off nt
	global_store_dword v[0:1], v19, off nt
	s_branch .LBB0_1354
